# seams: pollers watch the top-level arrival counter (TOP >= (gen+1)*nx) instead of the generation word bumped after the last leader's atomic returns
# baseline (speedup 1.0000x reference)
; __device__ __forceinline__ unsigned xb_ld(unsigned* p)              { return __hip_atomic_load(p, __ATOMIC_RELAXED, __HIP_MEMORY_SCOPE_AGENT); }
; __device__ __forceinline__ unsigned xb_add(unsigned* p, unsigned v) { return __hip_atomic_fetch_add(p, v, __ATOMIC_RELAXED, __HIP_MEMORY_SCOPE_AGENT); }
; #define XB_SPIN(cond, bar) do { unsigned _sp = 0; while (cond) { __builtin_amdgcn_s_sleep(1); \
;     if ((++_sp & 255u) == 0u) { if (xb_ld(&(bar)[XB_TMO])) break; if (_sp > XB_SPIN_CAP) { atomicAdd(&(bar)[XB_TMO], 1u); break; } } } } while (0)
; __device__ __forceinline__ void xcd_barrier(const XcdBarrier& b) {
;     ...
;         const unsigned old = xb_add(&bar[XB_XSUB(b.x)], 1u);
;         const unsigned gen = old / nloc;
;         if (old + 1u == (gen + 1u) * nloc) {
;             __builtin_amdgcn_fence(__ATOMIC_RELEASE, "agent");
;             asm volatile("s_waitcnt vmcnt(0)" ::: "memory");
;             const unsigned og = xb_add(&bar[XB_TOP], 1u);
;             const unsigned tg = og / nx;
;             if (og + 1u == (tg + 1u) * nx) xb_add(&bar[XB_TOPGEN], 1u);
;             else XB_SPIN(xb_ld(&bar[XB_TOPGEN]) == tg, bar);
;             __builtin_amdgcn_fence(__ATOMIC_ACQUIRE, "agent");
;             asm volatile("s_waitcnt vmcnt(0)" ::: "memory");
;         } else {
;             XB_SPIN(xb_ld(&bar[XB_TOPGEN]) == gen, bar);
.LBB0_45:
	s_or_b64 exec, exec, s[6:7]
	buffer_inv sc1
	v_cvt_f32_u32_e32 v5, v3
	s_waitcnt vmcnt(0)
	v_readfirstlane_b32 s8, v4
	s_add_u32 s6, s86, 0x3500
	s_addc_u32 s7, s87, 0
	v_rcp_iflag_f32_e32 v5, v5
	v_add_u32_e32 v6, s8, v2
	v_mul_f32_e32 v4, 0x4f7ffffe, v5
	v_cvt_u32_f32_e32 v4, v4
	v_sub_u32_e32 v5, 0, v3
	v_mul_lo_u32 v2, v5, v4
	v_mul_hi_u32 v2, v4, v2
	v_add_u32_e32 v2, v4, v2
	v_mul_hi_u32 v2, v6, v2
	v_mul_lo_u32 v4, v2, v3
	v_sub_u32_e32 v4, v6, v4
	v_add_u32_e32 v5, 1, v2
	v_cmp_ge_u32_e32 vcc, v4, v3
	s_nop 1
	v_cndmask_b32_e32 v2, v2, v5, vcc
	v_sub_u32_e32 v5, v4, v3
	v_cndmask_b32_e32 v4, v4, v5, vcc
	v_add_u32_e32 v5, 1, v2
	v_cmp_ge_u32_e32 vcc, v4, v3
	v_add_u32_e32 v4, 1, v6
	s_nop 0
	v_cndmask_b32_e32 v2, v2, v5, vcc
	v_mul_lo_u32 v5, v3, v2
	v_add_u32_e32 v3, v5, v3
	v_cmp_ne_u32_e32 vcc, v4, v3
	s_and_saveexec_b64 s[8:9], vcc
	s_xor_b64 s[8:9], exec, s[8:9]
	s_cbranch_execz .LBB0_59
	s_waitcnt lgkmcnt(0)
	v_mad_u32_u24 v2, v2, v1, v1
	v_mov_b32_e32 v1, 0
	global_load_dword v3, v1, s[6:7] offset:-256 sc1
	s_waitcnt vmcnt(0)
	v_cmp_lt_u32_e32 vcc, v3, v2
	s_and_saveexec_b64 s[10:11], vcc
	s_cbranch_execz .LBB0_58
	s_mov_b32 s22, 1
	s_mov_b64 s[12:13], 0
	s_branch .LBB0_49

; __device__ __forceinline__ unsigned xb_ld(unsigned* p)              { return __hip_atomic_load(p, __ATOMIC_RELAXED, __HIP_MEMORY_SCOPE_AGENT); }
; #define XB_SPIN(cond, bar) do { unsigned _sp = 0; while (cond) { __builtin_amdgcn_s_sleep(1); \
;     if ((++_sp & 255u) == 0u) { if (xb_ld(&(bar)[XB_TMO])) break; if (_sp > XB_SPIN_CAP) { atomicAdd(&(bar)[XB_TMO], 1u); break; } } } } while (0)
; __device__ __forceinline__ void xcd_barrier(const XcdBarrier& b) {
;     ...
;             XB_SPIN(xb_ld(&bar[XB_TOPGEN]) == gen, bar);
.LBB0_51:
	global_load_dword v3, v1, s[6:7] offset:-256 sc1
	s_add_i32 s22, s22, 1
	s_mov_b64 s[18:19], -1
	s_waitcnt vmcnt(0)
	v_cmp_ge_u32_e32 vcc, v3, v2
	s_orn2_b64 s[16:17], vcc, exec
	s_branch .LBB0_48

; __device__ __forceinline__ unsigned xb_ld(unsigned* p)              { return __hip_atomic_load(p, __ATOMIC_RELAXED, __HIP_MEMORY_SCOPE_AGENT); }
; __device__ __forceinline__ unsigned xb_add(unsigned* p, unsigned v) { return __hip_atomic_fetch_add(p, v, __ATOMIC_RELAXED, __HIP_MEMORY_SCOPE_AGENT); }
; #define XB_SPIN(cond, bar) do { unsigned _sp = 0; while (cond) { __builtin_amdgcn_s_sleep(1); \
;     if ((++_sp & 255u) == 0u) { if (xb_ld(&(bar)[XB_TMO])) break; if (_sp > XB_SPIN_CAP) { atomicAdd(&(bar)[XB_TMO], 1u); break; } } } } while (0)
; __device__ __forceinline__ void xcd_barrier(const XcdBarrier& b) {
;     ...
;             const unsigned og = xb_add(&bar[XB_TOP], 1u);
;             const unsigned tg = og / nx;
;             if (og + 1u == (tg + 1u) * nx) xb_add(&bar[XB_TOPGEN], 1u);
;             else XB_SPIN(xb_ld(&bar[XB_TOPGEN]) == tg, bar);
.LBB0_62:
	s_or_b64 exec, exec, s[10:11]
	v_cvt_f32_u32_e32 v4, v1
	s_waitcnt vmcnt(0)
	v_readfirstlane_b32 s8, v3
	s_mov_b64 s[10:11], -1
	v_rcp_iflag_f32_e32 v4, v4
	v_add_u32_e32 v2, s8, v2
	v_add_u32_e32 v5, 1, v2
	v_mul_f32_e32 v3, 0x4f7ffffe, v4
	v_cvt_u32_f32_e32 v3, v3
	v_sub_u32_e32 v4, 0, v1
	v_mul_lo_u32 v4, v4, v3
	v_mul_hi_u32 v4, v3, v4
	v_add_u32_e32 v3, v3, v4
	v_mul_hi_u32 v3, v2, v3
	v_mul_lo_u32 v4, v3, v1
	v_sub_u32_e32 v2, v2, v4
	v_add_u32_e32 v6, 1, v3
	v_cmp_ge_u32_e32 vcc, v2, v1
	v_sub_u32_e32 v4, v2, v1
	s_nop 0
	v_cndmask_b32_e32 v3, v3, v6, vcc
	v_cndmask_b32_e32 v2, v2, v4, vcc
	v_add_u32_e32 v4, 1, v3
	v_cmp_ge_u32_e32 vcc, v2, v1
	s_nop 1
	v_cndmask_b32_e32 v4, v3, v4, vcc
	v_mul_lo_u32 v2, v1, v4
	v_add_u32_e32 v1, v2, v1
	v_cmp_ne_u32_e32 vcc, v5, v1
	v_mov_b64_e32 v[2:3], s[6:7]
	s_and_saveexec_b64 s[8:9], vcc
	s_cbranch_execz .LBB0_74
	v_mov_b32_e32 v4, v1
	v_mov_b32_e32 v1, 0
	global_load_dword v2, v1, s[6:7] offset:-256 sc1
	s_mov_b64 s[12:13], 0
	s_waitcnt vmcnt(0)
	v_cmp_lt_u32_e32 vcc, v2, v4
	s_and_saveexec_b64 s[10:11], vcc
	s_cbranch_execz .LBB0_73
	s_mov_b32 s22, 1
	s_branch .LBB0_66

; __device__ __forceinline__ unsigned xb_ld(unsigned* p)              { return __hip_atomic_load(p, __ATOMIC_RELAXED, __HIP_MEMORY_SCOPE_AGENT); }
; #define XB_SPIN(cond, bar) do { unsigned _sp = 0; while (cond) { __builtin_amdgcn_s_sleep(1); \
;     if ((++_sp & 255u) == 0u) { if (xb_ld(&(bar)[XB_TMO])) break; if (_sp > XB_SPIN_CAP) { atomicAdd(&(bar)[XB_TMO], 1u); break; } } } } while (0)
; __device__ __forceinline__ void xcd_barrier(const XcdBarrier& b) {
;     ...
;             else XB_SPIN(xb_ld(&bar[XB_TOPGEN]) == tg, bar);
.LBB0_68:
	global_load_dword v2, v1, s[6:7] offset:-256 sc1
	s_add_i32 s22, s22, 1
	s_mov_b64 s[16:17], -1
	s_waitcnt vmcnt(0)
	v_cmp_ge_u32_e32 vcc, v2, v4
	s_orn2_b64 s[20:21], vcc, exec
	s_branch .LBB0_65

; __device__ __forceinline__ unsigned xb_ld(unsigned* p)              { return __hip_atomic_load(p, __ATOMIC_RELAXED, __HIP_MEMORY_SCOPE_AGENT); }
; __device__ __forceinline__ unsigned xb_add(unsigned* p, unsigned v) { return __hip_atomic_fetch_add(p, v, __ATOMIC_RELAXED, __HIP_MEMORY_SCOPE_AGENT); }
; #define XB_SPIN(cond, bar) do { unsigned _sp = 0; while (cond) { __builtin_amdgcn_s_sleep(1); \
;     if ((++_sp & 255u) == 0u) { if (xb_ld(&(bar)[XB_TMO])) break; if (_sp > XB_SPIN_CAP) { atomicAdd(&(bar)[XB_TMO], 1u); break; } } } } while (0)
; __device__ __forceinline__ void xcd_barrier(const XcdBarrier& b) {
;     ...
;         const unsigned old = xb_add(&bar[XB_XSUB(b.x)], 1u);
;         const unsigned gen = old / nloc;
;         if (old + 1u == (gen + 1u) * nloc) {
;             __builtin_amdgcn_fence(__ATOMIC_RELEASE, "agent");
;             asm volatile("s_waitcnt vmcnt(0)" ::: "memory");
;             const unsigned og = xb_add(&bar[XB_TOP], 1u);
;             const unsigned tg = og / nx;
;             if (og + 1u == (tg + 1u) * nx) xb_add(&bar[XB_TOPGEN], 1u);
;             else XB_SPIN(xb_ld(&bar[XB_TOPGEN]) == tg, bar);
;             __builtin_amdgcn_fence(__ATOMIC_ACQUIRE, "agent");
;             asm volatile("s_waitcnt vmcnt(0)" ::: "memory");
;         } else {
;             XB_SPIN(xb_ld(&bar[XB_TOPGEN]) == gen, bar);
.LBB0_218:
	s_or_b64 exec, exec, s[4:5]
	buffer_inv sc1
	v_cvt_f32_u32_e32 v5, v3
	s_waitcnt vmcnt(0)
	v_readfirstlane_b32 s6, v4
	s_add_u32 s4, s86, 0x3500
	s_addc_u32 s5, s87, 0
	v_rcp_iflag_f32_e32 v5, v5
	v_add_u32_e32 v6, s6, v2
	v_mul_f32_e32 v4, 0x4f7ffffe, v5
	v_cvt_u32_f32_e32 v4, v4
	v_sub_u32_e32 v5, 0, v3
	v_mul_lo_u32 v2, v5, v4
	v_mul_hi_u32 v2, v4, v2
	v_add_u32_e32 v2, v4, v2
	v_mul_hi_u32 v2, v6, v2
	v_mul_lo_u32 v4, v2, v3
	v_sub_u32_e32 v4, v6, v4
	v_add_u32_e32 v5, 1, v2
	v_cmp_ge_u32_e32 vcc, v4, v3
	s_nop 1
	v_cndmask_b32_e32 v2, v2, v5, vcc
	v_sub_u32_e32 v5, v4, v3
	v_cndmask_b32_e32 v4, v4, v5, vcc
	v_add_u32_e32 v5, 1, v2
	v_cmp_ge_u32_e32 vcc, v4, v3
	v_add_u32_e32 v4, 1, v6
	s_nop 0
	v_cndmask_b32_e32 v2, v2, v5, vcc
	v_mul_lo_u32 v5, v3, v2
	v_add_u32_e32 v3, v5, v3
	v_cmp_ne_u32_e32 vcc, v4, v3
	s_and_saveexec_b64 s[6:7], vcc
	s_xor_b64 s[6:7], exec, s[6:7]
	s_cbranch_execz .LBB0_232
	s_waitcnt lgkmcnt(0)
	v_mad_u32_u24 v2, v2, v1, v1
	v_mov_b32_e32 v1, 0
	global_load_dword v3, v1, s[4:5] offset:-256 sc1
	s_waitcnt vmcnt(0)
	v_cmp_lt_u32_e32 vcc, v3, v2
	s_and_saveexec_b64 s[8:9], vcc
	s_cbranch_execz .LBB0_231
	s_mov_b32 s20, 1
	s_mov_b64 s[10:11], 0
	s_branch .LBB0_222

; __device__ __forceinline__ unsigned xb_ld(unsigned* p)              { return __hip_atomic_load(p, __ATOMIC_RELAXED, __HIP_MEMORY_SCOPE_AGENT); }
; #define XB_SPIN(cond, bar) do { unsigned _sp = 0; while (cond) { __builtin_amdgcn_s_sleep(1); \
;     if ((++_sp & 255u) == 0u) { if (xb_ld(&(bar)[XB_TMO])) break; if (_sp > XB_SPIN_CAP) { atomicAdd(&(bar)[XB_TMO], 1u); break; } } } } while (0)
; __device__ __forceinline__ void xcd_barrier(const XcdBarrier& b) {
;     ...
;             XB_SPIN(xb_ld(&bar[XB_TOPGEN]) == gen, bar);
.LBB0_224:
	global_load_dword v3, v1, s[4:5] offset:-256 sc1
	s_add_i32 s20, s20, 1
	s_mov_b64 s[16:17], -1
	s_waitcnt vmcnt(0)
	v_cmp_ge_u32_e32 vcc, v3, v2
	s_orn2_b64 s[14:15], vcc, exec
	s_branch .LBB0_221

; __device__ __forceinline__ unsigned xb_ld(unsigned* p)              { return __hip_atomic_load(p, __ATOMIC_RELAXED, __HIP_MEMORY_SCOPE_AGENT); }
; __device__ __forceinline__ unsigned xb_add(unsigned* p, unsigned v) { return __hip_atomic_fetch_add(p, v, __ATOMIC_RELAXED, __HIP_MEMORY_SCOPE_AGENT); }
; #define XB_SPIN(cond, bar) do { unsigned _sp = 0; while (cond) { __builtin_amdgcn_s_sleep(1); \
;     if ((++_sp & 255u) == 0u) { if (xb_ld(&(bar)[XB_TMO])) break; if (_sp > XB_SPIN_CAP) { atomicAdd(&(bar)[XB_TMO], 1u); break; } } } } while (0)
; __device__ __forceinline__ void xcd_barrier(const XcdBarrier& b) {
;     ...
;             const unsigned og = xb_add(&bar[XB_TOP], 1u);
;             const unsigned tg = og / nx;
;             if (og + 1u == (tg + 1u) * nx) xb_add(&bar[XB_TOPGEN], 1u);
;             else XB_SPIN(xb_ld(&bar[XB_TOPGEN]) == tg, bar);
.LBB0_235:
	s_or_b64 exec, exec, s[8:9]
	v_cvt_f32_u32_e32 v4, v1
	s_waitcnt vmcnt(0)
	v_readfirstlane_b32 s6, v3
	s_mov_b64 s[8:9], -1
	v_rcp_iflag_f32_e32 v4, v4
	v_add_u32_e32 v2, s6, v2
	v_add_u32_e32 v5, 1, v2
	v_mul_f32_e32 v3, 0x4f7ffffe, v4
	v_cvt_u32_f32_e32 v3, v3
	v_sub_u32_e32 v4, 0, v1
	v_mul_lo_u32 v4, v4, v3
	v_mul_hi_u32 v4, v3, v4
	v_add_u32_e32 v3, v3, v4
	v_mul_hi_u32 v3, v2, v3
	v_mul_lo_u32 v4, v3, v1
	v_sub_u32_e32 v2, v2, v4
	v_add_u32_e32 v6, 1, v3
	v_cmp_ge_u32_e32 vcc, v2, v1
	v_sub_u32_e32 v4, v2, v1
	s_nop 0
	v_cndmask_b32_e32 v3, v3, v6, vcc
	v_cndmask_b32_e32 v2, v2, v4, vcc
	v_add_u32_e32 v4, 1, v3
	v_cmp_ge_u32_e32 vcc, v2, v1
	s_nop 1
	v_cndmask_b32_e32 v4, v3, v4, vcc
	v_mul_lo_u32 v2, v1, v4
	v_add_u32_e32 v1, v2, v1
	v_cmp_ne_u32_e32 vcc, v5, v1
	v_mov_b64_e32 v[2:3], s[4:5]
	s_and_saveexec_b64 s[6:7], vcc
	s_cbranch_execz .LBB0_247
	v_mov_b32_e32 v4, v1
	v_mov_b32_e32 v1, 0
	global_load_dword v2, v1, s[4:5] offset:-256 sc1
	s_mov_b64 s[10:11], 0
	s_waitcnt vmcnt(0)
	v_cmp_lt_u32_e32 vcc, v2, v4
	s_and_saveexec_b64 s[8:9], vcc
	s_cbranch_execz .LBB0_246
	s_mov_b32 s20, 1
	s_branch .LBB0_239

; __device__ __forceinline__ unsigned xb_ld(unsigned* p)              { return __hip_atomic_load(p, __ATOMIC_RELAXED, __HIP_MEMORY_SCOPE_AGENT); }
; #define XB_SPIN(cond, bar) do { unsigned _sp = 0; while (cond) { __builtin_amdgcn_s_sleep(1); \
;     if ((++_sp & 255u) == 0u) { if (xb_ld(&(bar)[XB_TMO])) break; if (_sp > XB_SPIN_CAP) { atomicAdd(&(bar)[XB_TMO], 1u); break; } } } } while (0)
; __device__ __forceinline__ void xcd_barrier(const XcdBarrier& b) {
;     ...
;             else XB_SPIN(xb_ld(&bar[XB_TOPGEN]) == tg, bar);
.LBB0_241:
	global_load_dword v2, v1, s[4:5] offset:-256 sc1
	s_add_i32 s20, s20, 1
	s_mov_b64 s[14:15], -1
	s_waitcnt vmcnt(0)
	v_cmp_ge_u32_e32 vcc, v2, v4
	s_orn2_b64 s[18:19], vcc, exec
	s_branch .LBB0_238
